# P0a transposes: 32 loads in flight + nt (non-temporal) hint on the f32 weight tile loads
# baseline (speedup 1.0000x reference)
.LBB0_18:
	s_mov_b32 s62, 0x4000
	s_mov_b32 s66, 0x8000
	s_mov_b32 s67, 0
	v_mad_u32_u24 v142, v38, s21, v44
	v_mad_u64_u32 v[140:141], s[64:65], v4, s62, v[2:3]
	global_load_dword v100, v[140:141], off nt
	v_lshl_add_u64 v[140:141], v[140:141], 0, s[66:67]
	global_load_dword v101, v[140:141], off nt
	v_lshl_add_u64 v[140:141], v[140:141], 0, s[66:67]
	global_load_dword v102, v[140:141], off nt
	v_lshl_add_u64 v[140:141], v[140:141], 0, s[66:67]
	global_load_dword v103, v[140:141], off nt
	v_lshl_add_u64 v[140:141], v[140:141], 0, s[66:67]
	global_load_dword v104, v[140:141], off nt
	v_lshl_add_u64 v[140:141], v[140:141], 0, s[66:67]
	global_load_dword v105, v[140:141], off nt
	v_lshl_add_u64 v[140:141], v[140:141], 0, s[66:67]
	global_load_dword v106, v[140:141], off nt
	v_lshl_add_u64 v[140:141], v[140:141], 0, s[66:67]
	global_load_dword v107, v[140:141], off nt
	v_lshl_add_u64 v[140:141], v[140:141], 0, s[66:67]
	global_load_dword v108, v[140:141], off nt
	v_lshl_add_u64 v[140:141], v[140:141], 0, s[66:67]
	global_load_dword v109, v[140:141], off nt
	v_lshl_add_u64 v[140:141], v[140:141], 0, s[66:67]
	global_load_dword v110, v[140:141], off nt
	v_lshl_add_u64 v[140:141], v[140:141], 0, s[66:67]
	global_load_dword v111, v[140:141], off nt
	v_lshl_add_u64 v[140:141], v[140:141], 0, s[66:67]
	global_load_dword v112, v[140:141], off nt
	v_lshl_add_u64 v[140:141], v[140:141], 0, s[66:67]
	global_load_dword v113, v[140:141], off nt
	v_lshl_add_u64 v[140:141], v[140:141], 0, s[66:67]
	global_load_dword v114, v[140:141], off nt
	v_lshl_add_u64 v[140:141], v[140:141], 0, s[66:67]
	global_load_dword v115, v[140:141], off nt
	v_lshl_add_u64 v[140:141], v[140:141], 0, s[66:67]
	global_load_dword v116, v[140:141], off nt
	v_lshl_add_u64 v[140:141], v[140:141], 0, s[66:67]
	global_load_dword v117, v[140:141], off nt
	v_lshl_add_u64 v[140:141], v[140:141], 0, s[66:67]
	global_load_dword v118, v[140:141], off nt
	v_lshl_add_u64 v[140:141], v[140:141], 0, s[66:67]
	global_load_dword v119, v[140:141], off nt
	v_lshl_add_u64 v[140:141], v[140:141], 0, s[66:67]
	global_load_dword v120, v[140:141], off nt
	v_lshl_add_u64 v[140:141], v[140:141], 0, s[66:67]
	global_load_dword v121, v[140:141], off nt
	v_lshl_add_u64 v[140:141], v[140:141], 0, s[66:67]
	global_load_dword v122, v[140:141], off nt
	v_lshl_add_u64 v[140:141], v[140:141], 0, s[66:67]
	global_load_dword v123, v[140:141], off nt
	v_lshl_add_u64 v[140:141], v[140:141], 0, s[66:67]
	global_load_dword v124, v[140:141], off nt
	v_lshl_add_u64 v[140:141], v[140:141], 0, s[66:67]
	global_load_dword v125, v[140:141], off nt
	v_lshl_add_u64 v[140:141], v[140:141], 0, s[66:67]
	global_load_dword v126, v[140:141], off nt
	v_lshl_add_u64 v[140:141], v[140:141], 0, s[66:67]
	global_load_dword v127, v[140:141], off nt
	v_lshl_add_u64 v[140:141], v[140:141], 0, s[66:67]
	global_load_dword v128, v[140:141], off nt
	v_lshl_add_u64 v[140:141], v[140:141], 0, s[66:67]
	global_load_dword v129, v[140:141], off nt
	v_lshl_add_u64 v[140:141], v[140:141], 0, s[66:67]
	global_load_dword v130, v[140:141], off nt
	v_lshl_add_u64 v[140:141], v[140:141], 0, s[66:67]
	global_load_dword v131, v[140:141], off nt
	s_waitcnt vmcnt(28)
	v_pk_mul_f32 v[100:101], v[100:101], s[20:21] op_sel_hi:[1,0]
	v_pk_mul_f32 v[102:103], v[102:103], s[20:21] op_sel_hi:[1,0]
	ds_write_b32 v142, v100
	ds_write_b32 v142, v101 offset:264
	ds_write_b32 v142, v102 offset:528
	ds_write_b32 v142, v103 offset:792
	s_waitcnt vmcnt(24)
	v_pk_mul_f32 v[104:105], v[104:105], s[20:21] op_sel_hi:[1,0]
	v_pk_mul_f32 v[106:107], v[106:107], s[20:21] op_sel_hi:[1,0]
	ds_write_b32 v142, v104 offset:1056
	ds_write_b32 v142, v105 offset:1320
	ds_write_b32 v142, v106 offset:1584
	ds_write_b32 v142, v107 offset:1848
	s_waitcnt vmcnt(20)
	v_pk_mul_f32 v[108:109], v[108:109], s[20:21] op_sel_hi:[1,0]
	v_pk_mul_f32 v[110:111], v[110:111], s[20:21] op_sel_hi:[1,0]
	ds_write_b32 v142, v108 offset:2112
	ds_write_b32 v142, v109 offset:2376
	ds_write_b32 v142, v110 offset:2640
	ds_write_b32 v142, v111 offset:2904
	s_waitcnt vmcnt(16)
	v_pk_mul_f32 v[112:113], v[112:113], s[20:21] op_sel_hi:[1,0]
	v_pk_mul_f32 v[114:115], v[114:115], s[20:21] op_sel_hi:[1,0]
	ds_write_b32 v142, v112 offset:3168
	ds_write_b32 v142, v113 offset:3432
	ds_write_b32 v142, v114 offset:3696
	ds_write_b32 v142, v115 offset:3960
	s_waitcnt vmcnt(12)
	v_pk_mul_f32 v[116:117], v[116:117], s[20:21] op_sel_hi:[1,0]
	v_pk_mul_f32 v[118:119], v[118:119], s[20:21] op_sel_hi:[1,0]
	ds_write_b32 v142, v116 offset:4224
	ds_write_b32 v142, v117 offset:4488
	ds_write_b32 v142, v118 offset:4752
	ds_write_b32 v142, v119 offset:5016
	s_waitcnt vmcnt(8)
	v_pk_mul_f32 v[120:121], v[120:121], s[20:21] op_sel_hi:[1,0]
	v_pk_mul_f32 v[122:123], v[122:123], s[20:21] op_sel_hi:[1,0]
	ds_write_b32 v142, v120 offset:5280
	ds_write_b32 v142, v121 offset:5544
	ds_write_b32 v142, v122 offset:5808
	ds_write_b32 v142, v123 offset:6072
	s_waitcnt vmcnt(4)
	v_pk_mul_f32 v[124:125], v[124:125], s[20:21] op_sel_hi:[1,0]
	v_pk_mul_f32 v[126:127], v[126:127], s[20:21] op_sel_hi:[1,0]
	ds_write_b32 v142, v124 offset:6336
	ds_write_b32 v142, v125 offset:6600
	ds_write_b32 v142, v126 offset:6864
	ds_write_b32 v142, v127 offset:7128
	s_waitcnt vmcnt(0)
	v_pk_mul_f32 v[128:129], v[128:129], s[20:21] op_sel_hi:[1,0]
	v_pk_mul_f32 v[130:131], v[130:131], s[20:21] op_sel_hi:[1,0]
	ds_write_b32 v142, v128 offset:7392
	ds_write_b32 v142, v129 offset:7656
	ds_write_b32 v142, v130 offset:7920
	ds_write_b32 v142, v131 offset:8184
	s_waitcnt lgkmcnt(0)
	ds_read2_b32 v[6:7], v59 offset1:16
	ds_read2_b32 v[8:9], v59 offset0:33 offset1:49
	ds_read2_b32 v[10:11], v59 offset0:66 offset1:82
	ds_read2_b32 v[12:13], v59 offset0:99 offset1:115
	ds_read2_b32 v[16:17], v59 offset0:132 offset1:148
	ds_read2_b32 v[18:19], v59 offset0:165 offset1:181
	ds_read2_b32 v[20:21], v59 offset0:198 offset1:214
	ds_read2_b32 v[22:23], v59 offset0:231 offset1:247
	s_waitcnt lgkmcnt(7)
	v_max_f32_e32 v2, v6, v6
	s_waitcnt lgkmcnt(6)
	v_max_f32_e32 v3, v8, v8
	v_med3_f32 v6, v2, s39, v77
	v_med3_f32 v3, v3, s39, v77
	v_mov_b32_e32 v2, v35
	v_cvt_pk_fp8_f32 v2, v6, v3
	s_waitcnt lgkmcnt(5)
	v_max_f32_e32 v4, v10, v10
	s_waitcnt lgkmcnt(4)
	v_max_f32_e32 v5, v12, v12
	v_med3_f32 v4, v4, s39, v77
	v_med3_f32 v5, v5, s39, v77
	v_cvt_pk_fp8_f32 v2, v4, v5 op_sel:[0,0,1]
	s_waitcnt lgkmcnt(3)
	v_max_f32_e32 v3, v16, v16
	s_waitcnt lgkmcnt(2)
	v_max_f32_e32 v4, v18, v18
	v_med3_f32 v8, v3, s39, v77
	v_med3_f32 v4, v4, s39, v77
	v_mov_b32_e32 v3, v35
	v_cvt_pk_fp8_f32 v3, v8, v4
	v_add_u32_e32 v8, 0x400, v59
	ds_read2_b32 v[24:25], v8 offset0:8 offset1:24
	ds_read2_b32 v[26:27], v8 offset0:41 offset1:57
	ds_read2_b32 v[28:29], v8 offset0:74 offset1:90
	ds_read2_b32 v[30:31], v8 offset0:107 offset1:123
	s_waitcnt lgkmcnt(5)
	v_max_f32_e32 v5, v20, v20
	s_waitcnt lgkmcnt(4)
	v_max_f32_e32 v6, v22, v22
	v_med3_f32 v5, v5, s39, v77
	v_med3_f32 v6, v6, s39, v77
	v_cvt_pk_fp8_f32 v3, v5, v6 op_sel:[0,0,1]
	s_waitcnt lgkmcnt(3)
	v_max_f32_e32 v4, v24, v24
	s_waitcnt lgkmcnt(2)
	v_max_f32_e32 v5, v26, v26
	v_med3_f32 v12, v4, s39, v77
	v_med3_f32 v5, v5, s39, v77
	v_mov_b32_e32 v4, v35
	v_cvt_pk_fp8_f32 v4, v12, v5
	ds_read2_b32 v[32:33], v8 offset0:140 offset1:156
	ds_read2_b32 v[80:81], v8 offset0:173 offset1:189
	ds_read2_b32 v[82:83], v8 offset0:206 offset1:222
	s_waitcnt lgkmcnt(4)
	v_max_f32_e32 v6, v28, v28
	s_waitcnt lgkmcnt(3)
	v_max_f32_e32 v10, v30, v30
	v_med3_f32 v6, v6, s39, v77
	v_med3_f32 v5, v10, s39, v77
	ds_read2_b32 v[84:85], v8 offset0:239 offset1:255
	v_cvt_pk_fp8_f32 v4, v6, v5 op_sel:[0,0,1]
	s_waitcnt lgkmcnt(3)
	v_max_f32_e32 v5, v32, v32
	s_waitcnt lgkmcnt(2)
	v_max_f32_e32 v6, v80, v80
	v_med3_f32 v8, v5, s39, v77
	v_med3_f32 v6, v6, s39, v77
	v_mov_b32_e32 v5, v35
	v_cvt_pk_fp8_f32 v5, v8, v6
	s_waitcnt lgkmcnt(1)
	v_max_f32_e32 v10, v82, v82
	s_waitcnt lgkmcnt(0)
	v_max_f32_e32 v6, v84, v84
	v_med3_f32 v8, v10, s39, v77
	v_med3_f32 v6, v6, s39, v77
	v_cvt_pk_fp8_f32 v5, v8, v6 op_sel:[0,0,1]
	v_or_b32_e32 v6, s6, v45
	v_lshl_add_u64 v[14:15], v[46:47], 0, s[16:17]
	v_lshlrev_b32_e32 v34, 14, v6
	v_lshl_add_u64 v[86:87], v[14:15], 0, v[34:35]
	global_store_dwordx4 v[86:87], v[2:5], off
	s_nop 1
	v_max_f32_e32 v2, v7, v7
	v_max_f32_e32 v3, v9, v9
	v_med3_f32 v5, v2, s39, v77
	v_med3_f32 v3, v3, s39, v77
	v_mov_b32_e32 v2, v35
	v_cvt_pk_fp8_f32 v2, v5, v3
	v_max_f32_e32 v4, v11, v11
	v_max_f32_e32 v3, v13, v13
	v_med3_f32 v4, v4, s39, v77
	v_med3_f32 v3, v3, s39, v77
	v_cvt_pk_fp8_f32 v2, v4, v3 op_sel:[0,0,1]
	v_max_f32_e32 v3, v17, v17
	v_max_f32_e32 v4, v19, v19
	v_med3_f32 v6, v3, s39, v77
	v_med3_f32 v4, v4, s39, v77
	v_mov_b32_e32 v3, v35
	v_cvt_pk_fp8_f32 v3, v6, v4
	v_max_f32_e32 v5, v21, v21
	v_max_f32_e32 v4, v23, v23
	v_med3_f32 v5, v5, s39, v77
	v_med3_f32 v4, v4, s39, v77
	v_cvt_pk_fp8_f32 v3, v5, v4 op_sel:[0,0,1]
	v_max_f32_e32 v4, v25, v25
	v_max_f32_e32 v5, v27, v27
	v_med3_f32 v7, v4, s39, v77
	v_med3_f32 v5, v5, s39, v77
	v_mov_b32_e32 v4, v35
	v_cvt_pk_fp8_f32 v4, v7, v5
	v_max_f32_e32 v6, v29, v29
	v_max_f32_e32 v5, v31, v31
	v_med3_f32 v6, v6, s39, v77
	v_med3_f32 v5, v5, s39, v77
	v_cvt_pk_fp8_f32 v4, v6, v5 op_sel:[0,0,1]
	v_max_f32_e32 v5, v33, v33
	v_max_f32_e32 v6, v81, v81
	v_med3_f32 v8, v5, s39, v77
	v_med3_f32 v6, v6, s39, v77
	v_mov_b32_e32 v5, v35
	v_cvt_pk_fp8_f32 v5, v8, v6
	v_max_f32_e32 v7, v83, v83
	v_max_f32_e32 v6, v85, v85
	v_med3_f32 v7, v7, s39, v77
	v_med3_f32 v6, v6, s39, v77
	v_cvt_pk_fp8_f32 v5, v7, v6 op_sel:[0,0,1]
	v_or_b32_e32 v6, s6, v62
	v_lshlrev_b32_e32 v34, 14, v6
	v_lshl_add_u64 v[6:7], v[14:15], 0, v[34:35]
	global_store_dwordx4 v[6:7], v[2:5], off
	s_waitcnt lgkmcnt(0)
	s_mov_b64 s[6:7], 0

.LBB0_22:
	s_mov_b32 s62, 0x10000
	s_mov_b32 s66, 0x20000
	s_mov_b32 s67, 0
	v_mad_u32_u24 v142, v38, s21, v44
	v_mad_u64_u32 v[140:141], s[64:65], v4, s62, v[2:3]
	global_load_dword v100, v[140:141], off nt
	v_lshl_add_u64 v[140:141], v[140:141], 0, s[66:67]
	global_load_dword v101, v[140:141], off nt
	v_lshl_add_u64 v[140:141], v[140:141], 0, s[66:67]
	global_load_dword v102, v[140:141], off nt
	v_lshl_add_u64 v[140:141], v[140:141], 0, s[66:67]
	global_load_dword v103, v[140:141], off nt
	v_lshl_add_u64 v[140:141], v[140:141], 0, s[66:67]
	global_load_dword v104, v[140:141], off nt
	v_lshl_add_u64 v[140:141], v[140:141], 0, s[66:67]
	global_load_dword v105, v[140:141], off nt
	v_lshl_add_u64 v[140:141], v[140:141], 0, s[66:67]
	global_load_dword v106, v[140:141], off nt
	v_lshl_add_u64 v[140:141], v[140:141], 0, s[66:67]
	global_load_dword v107, v[140:141], off nt
	v_lshl_add_u64 v[140:141], v[140:141], 0, s[66:67]
	global_load_dword v108, v[140:141], off nt
	v_lshl_add_u64 v[140:141], v[140:141], 0, s[66:67]
	global_load_dword v109, v[140:141], off nt
	v_lshl_add_u64 v[140:141], v[140:141], 0, s[66:67]
	global_load_dword v110, v[140:141], off nt
	v_lshl_add_u64 v[140:141], v[140:141], 0, s[66:67]
	global_load_dword v111, v[140:141], off nt
	v_lshl_add_u64 v[140:141], v[140:141], 0, s[66:67]
	global_load_dword v112, v[140:141], off nt
	v_lshl_add_u64 v[140:141], v[140:141], 0, s[66:67]
	global_load_dword v113, v[140:141], off nt
	v_lshl_add_u64 v[140:141], v[140:141], 0, s[66:67]
	global_load_dword v114, v[140:141], off nt
	v_lshl_add_u64 v[140:141], v[140:141], 0, s[66:67]
	global_load_dword v115, v[140:141], off nt
	v_lshl_add_u64 v[140:141], v[140:141], 0, s[66:67]
	global_load_dword v116, v[140:141], off nt
	v_lshl_add_u64 v[140:141], v[140:141], 0, s[66:67]
	global_load_dword v117, v[140:141], off nt
	v_lshl_add_u64 v[140:141], v[140:141], 0, s[66:67]
	global_load_dword v118, v[140:141], off nt
	v_lshl_add_u64 v[140:141], v[140:141], 0, s[66:67]
	global_load_dword v119, v[140:141], off nt
	v_lshl_add_u64 v[140:141], v[140:141], 0, s[66:67]
	global_load_dword v120, v[140:141], off nt
	v_lshl_add_u64 v[140:141], v[140:141], 0, s[66:67]
	global_load_dword v121, v[140:141], off nt
	v_lshl_add_u64 v[140:141], v[140:141], 0, s[66:67]
	global_load_dword v122, v[140:141], off nt
	v_lshl_add_u64 v[140:141], v[140:141], 0, s[66:67]
	global_load_dword v123, v[140:141], off nt
	v_lshl_add_u64 v[140:141], v[140:141], 0, s[66:67]
	global_load_dword v124, v[140:141], off nt
	v_lshl_add_u64 v[140:141], v[140:141], 0, s[66:67]
	global_load_dword v125, v[140:141], off nt
	v_lshl_add_u64 v[140:141], v[140:141], 0, s[66:67]
	global_load_dword v126, v[140:141], off nt
	v_lshl_add_u64 v[140:141], v[140:141], 0, s[66:67]
	global_load_dword v127, v[140:141], off nt
	v_lshl_add_u64 v[140:141], v[140:141], 0, s[66:67]
	global_load_dword v128, v[140:141], off nt
	v_lshl_add_u64 v[140:141], v[140:141], 0, s[66:67]
	global_load_dword v129, v[140:141], off nt
	v_lshl_add_u64 v[140:141], v[140:141], 0, s[66:67]
	global_load_dword v130, v[140:141], off nt
	v_lshl_add_u64 v[140:141], v[140:141], 0, s[66:67]
	global_load_dword v131, v[140:141], off nt
	s_waitcnt vmcnt(28)
	ds_write_b32 v142, v100
	ds_write_b32 v142, v101 offset:264
	ds_write_b32 v142, v102 offset:528
	ds_write_b32 v142, v103 offset:792
	s_waitcnt vmcnt(24)
	ds_write_b32 v142, v104 offset:1056
	ds_write_b32 v142, v105 offset:1320
	ds_write_b32 v142, v106 offset:1584
	ds_write_b32 v142, v107 offset:1848
	s_waitcnt vmcnt(20)
	ds_write_b32 v142, v108 offset:2112
	ds_write_b32 v142, v109 offset:2376
	ds_write_b32 v142, v110 offset:2640
	ds_write_b32 v142, v111 offset:2904
	s_waitcnt vmcnt(16)
	ds_write_b32 v142, v112 offset:3168
	ds_write_b32 v142, v113 offset:3432
	ds_write_b32 v142, v114 offset:3696
	ds_write_b32 v142, v115 offset:3960
	s_waitcnt vmcnt(12)
	ds_write_b32 v142, v116 offset:4224
	ds_write_b32 v142, v117 offset:4488
	ds_write_b32 v142, v118 offset:4752
	ds_write_b32 v142, v119 offset:5016
	s_waitcnt vmcnt(8)
	ds_write_b32 v142, v120 offset:5280
	ds_write_b32 v142, v121 offset:5544
	ds_write_b32 v142, v122 offset:5808
	ds_write_b32 v142, v123 offset:6072
	s_waitcnt vmcnt(4)
	ds_write_b32 v142, v124 offset:6336
	ds_write_b32 v142, v125 offset:6600
	ds_write_b32 v142, v126 offset:6864
	ds_write_b32 v142, v127 offset:7128
	s_waitcnt vmcnt(0)
	ds_write_b32 v142, v128 offset:7392
	ds_write_b32 v142, v129 offset:7656
	ds_write_b32 v142, v130 offset:7920
	ds_write_b32 v142, v131 offset:8184
	s_waitcnt lgkmcnt(0)
	ds_read2_b32 v[2:3], v63 offset1:33
	v_add_u32_e32 v16, 0x800, v63
	v_add_u32_e32 v18, 0x400, v63
	v_add_u32_e32 v19, 0xc00, v63
	ds_read2_b32 v[4:5], v16 offset0:16 offset1:49
	ds_read2_b32 v[6:7], v63 offset0:66 offset1:99
	ds_read2_b32 v[8:9], v16 offset0:82 offset1:115
	ds_read2_b32 v[10:11], v63 offset0:132 offset1:165
	ds_read2_b32 v[12:13], v16 offset0:148 offset1:181
	ds_read2_b32 v[14:15], v63 offset0:198 offset1:231
	ds_read2_b32 v[16:17], v16 offset0:214 offset1:247
	ds_read2_b32 v[26:27], v18 offset0:8 offset1:41
	ds_read2_b32 v[28:29], v19 offset0:24 offset1:57
	ds_read2_b32 v[30:31], v18 offset0:74 offset1:107
	ds_read2_b32 v[32:33], v19 offset0:90 offset1:123
	ds_read2_b32 v[80:81], v18 offset0:140 offset1:173
	ds_read2_b32 v[82:83], v19 offset0:156 offset1:189
	ds_read2_b32 v[84:85], v18 offset0:206 offset1:239
	ds_read2_b32 v[86:87], v19 offset0:222 offset1:255
	s_waitcnt lgkmcnt(14)
	v_max_f32_e64 v18, |v4|, |v4|
	v_max_f32_e64 v19, |v2|, |v2|
	v_max_f32_e32 v18, v19, v18
	v_max_f32_e64 v19, |v5|, |v5|
	v_max_f32_e64 v20, |v3|, |v3|
	v_max_f32_e32 v19, v20, v19
	v_max3_f32 v18, v18, 0, v19
	s_waitcnt lgkmcnt(12)
	v_max_f32_e64 v19, |v8|, |v8|
	v_max_f32_e64 v20, |v6|, |v6|
	v_max_f32_e32 v19, v20, v19
	v_max_f32_e64 v20, |v9|, |v9|
	v_max_f32_e64 v21, |v7|, |v7|
	v_max_f32_e32 v20, v21, v20
	v_max3_f32 v18, v18, v19, v20
	s_waitcnt lgkmcnt(10)
	v_max_f32_e64 v19, |v12|, |v12|
	v_max_f32_e64 v20, |v10|, |v10|
	v_max_f32_e32 v19, v20, v19
	v_max_f32_e64 v20, |v13|, |v13|
	v_max_f32_e64 v21, |v11|, |v11|
	v_max_f32_e32 v20, v21, v20
	v_max3_f32 v18, v18, v19, v20
	s_waitcnt lgkmcnt(8)
	v_max_f32_e64 v19, |v16|, |v16|
	v_max_f32_e64 v20, |v14|, |v14|
	v_max_f32_e32 v19, v20, v19
	v_max_f32_e64 v20, |v17|, |v17|
	v_max_f32_e64 v21, |v15|, |v15|
	v_max_f32_e32 v20, v21, v20
	v_max3_f32 v18, v18, v19, v20
	s_waitcnt lgkmcnt(6)
	v_max_f32_e64 v19, |v28|, |v28|
	v_max_f32_e64 v20, |v26|, |v26|
	v_max_f32_e32 v19, v20, v19
	v_max_f32_e64 v20, |v29|, |v29|
	v_max_f32_e64 v21, |v27|, |v27|
	v_max_f32_e32 v20, v21, v20
	v_max3_f32 v18, v18, v19, v20
	s_waitcnt lgkmcnt(4)
	v_max_f32_e64 v19, |v32|, |v32|
	v_max_f32_e64 v20, |v30|, |v30|
	v_max_f32_e32 v19, v20, v19
	v_max_f32_e64 v20, |v33|, |v33|
	v_max_f32_e64 v21, |v31|, |v31|
	v_max_f32_e32 v20, v21, v20
	v_max3_f32 v18, v18, v19, v20
	s_waitcnt lgkmcnt(2)
	v_max_f32_e64 v19, |v82|, |v82|
	v_max_f32_e64 v20, |v80|, |v80|
	v_max_f32_e32 v19, v20, v19
	v_max_f32_e64 v20, |v83|, |v83|
	v_max_f32_e64 v21, |v81|, |v81|
	v_max_f32_e32 v20, v21, v20
	v_max3_f32 v18, v18, v19, v20
	s_waitcnt lgkmcnt(0)
	v_max_f32_e64 v19, |v86|, |v86|
	v_max_f32_e64 v20, |v84|, |v84|
	v_max_f32_e32 v19, v20, v19
	v_max_f32_e64 v20, |v87|, |v87|
	v_max_f32_e64 v21, |v85|, |v85|
	v_max_f32_e32 v20, v21, v20
	v_max3_f32 v18, v18, v19, v20
	v_bfe_u32 v18, v18, 23, 8
	v_max_u32_e32 v34, 3, v18
	v_lshlrev_b32_e32 v18, 23, v34
	v_sub_u32_e32 v61, 0x80000000, v18
	v_mul_f32_e32 v4, v4, v61
	v_med3_f32 v18, v4, s40, v78
	v_mul_f32_e32 v4, v5, v61
	v_mul_f32_e32 v5, v8, v61
	v_med3_f32 v19, v4, s40, v78
	v_mul_f32_e32 v4, v6, v61
	v_med3_f32 v20, v5, s40, v78
	v_mul_f32_e32 v5, v7, v61
	v_mul_f32_e32 v6, v9, v61
	v_mul_f32_e32 v7, v12, v61
	v_mul_f32_e32 v8, v13, v61
	v_mul_f32_e32 v9, v16, v61
	v_med3_f32 v21, v6, s40, v78
	v_mul_f32_e32 v6, v10, v61
	v_med3_f32 v22, v7, s40, v78
	v_mul_f32_e32 v7, v11, v61
	v_med3_f32 v23, v8, s40, v78
	v_mul_f32_e32 v8, v14, v61
	v_med3_f32 v24, v9, s40, v78
	v_mul_f32_e32 v9, v15, v61
	v_mul_f32_e32 v10, v17, v61
	v_mul_f32_e32 v11, v28, v61
	v_mul_f32_e32 v12, v29, v61
	v_mul_f32_e32 v13, v32, v61
	v_mul_f32_e32 v14, v33, v61
	v_mul_f32_e32 v15, v82, v61
	v_mul_f32_e32 v16, v83, v61
	v_mul_f32_e32 v17, v86, v61
	v_mul_f32_e32 v2, v2, v61
	v_mul_f32_e32 v3, v3, v61
	v_med3_f32 v25, v10, s40, v78
	v_mul_f32_e32 v10, v26, v61
	v_med3_f32 v26, v11, s40, v78
	v_mul_f32_e32 v11, v27, v61
	v_med3_f32 v27, v12, s40, v78
	v_mul_f32_e32 v12, v30, v61
	v_med3_f32 v28, v13, s40, v78
	v_mul_f32_e32 v13, v31, v61
	v_med3_f32 v29, v14, s40, v78
	v_mul_f32_e32 v14, v80, v61
	v_med3_f32 v30, v15, s40, v78
	v_mul_f32_e32 v15, v81, v61
	v_med3_f32 v31, v16, s40, v78
	v_mul_f32_e32 v16, v84, v61
	v_med3_f32 v32, v17, s40, v78
	v_mul_f32_e32 v17, v85, v61
	v_mul_f32_e32 v33, v87, v61
	v_med3_f32 v2, v2, s40, v78
	v_med3_f32 v3, v3, s40, v78
	v_med3_f32 v4, v4, s40, v78
	v_med3_f32 v5, v5, s40, v78
	v_med3_f32 v6, v6, s40, v78
	v_med3_f32 v7, v7, s40, v78
	v_med3_f32 v8, v8, s40, v78
	v_med3_f32 v9, v9, s40, v78
	v_med3_f32 v10, v10, s40, v78
	v_med3_f32 v11, v11, s40, v78
	v_med3_f32 v12, v12, s40, v78
	v_med3_f32 v13, v13, s40, v78
	v_med3_f32 v14, v14, s40, v78
	v_med3_f32 v15, v15, s40, v78
	v_med3_f32 v16, v16, s40, v78
	v_med3_f32 v17, v17, s40, v78
	v_med3_f32 v33, v33, s40, v78
	s_and_b32 s7, 0xffff, s7
	v_cvt_scalef32_2xpk16_fp6_f32 v[2:7], v[2:17], v[18:33], 1.0
	v_mov_b32_e32 v32, v6
	v_or_b32_e32 v6, s7, v40
	v_mov_b32_e32 v33, v7
	v_lshlrev_b32_e32 v6, 12, v6
	v_mov_b32_e32 v7, v35
	v_or_b32_e32 v8, s6, v41
	v_lshl_add_u64 v[6:7], s[18:19], 0, v[6:7]
	s_and_b32 s16, s6, 0x1f80
	v_lshrrev_b32_e32 v8, 1, v8
	v_and_b32_e32 v8, 48, v8
	v_mov_b32_e32 v9, v35
	v_lshl_add_u64 v[6:7], v[6:7], 0, s[16:17]
	v_lshl_add_u64 v[6:7], v[6:7], 0, v[8:9]
	v_add_u32_e32 v34, -2, v34
	global_store_dwordx4 v[6:7], v[2:5], off
	global_store_dwordx4 v[6:7], v[32:35], off offset:64
	s_waitcnt lgkmcnt(0)

.LBB0_28:
	s_mov_b32 s62, 0x4000
	s_mov_b32 s66, 0x8000
	s_mov_b32 s67, 0
	v_mad_u32_u24 v142, v38, s21, v44
	v_mad_u64_u32 v[140:141], s[64:65], v4, s62, v[2:3]
	global_load_dword v100, v[140:141], off nt
	v_lshl_add_u64 v[140:141], v[140:141], 0, s[66:67]
	global_load_dword v101, v[140:141], off nt
	v_lshl_add_u64 v[140:141], v[140:141], 0, s[66:67]
	global_load_dword v102, v[140:141], off nt
	v_lshl_add_u64 v[140:141], v[140:141], 0, s[66:67]
	global_load_dword v103, v[140:141], off nt
	v_lshl_add_u64 v[140:141], v[140:141], 0, s[66:67]
	global_load_dword v104, v[140:141], off nt
	v_lshl_add_u64 v[140:141], v[140:141], 0, s[66:67]
	global_load_dword v105, v[140:141], off nt
	v_lshl_add_u64 v[140:141], v[140:141], 0, s[66:67]
	global_load_dword v106, v[140:141], off nt
	v_lshl_add_u64 v[140:141], v[140:141], 0, s[66:67]
	global_load_dword v107, v[140:141], off nt
	v_lshl_add_u64 v[140:141], v[140:141], 0, s[66:67]
	global_load_dword v108, v[140:141], off nt
	v_lshl_add_u64 v[140:141], v[140:141], 0, s[66:67]
	global_load_dword v109, v[140:141], off nt
	v_lshl_add_u64 v[140:141], v[140:141], 0, s[66:67]
	global_load_dword v110, v[140:141], off nt
	v_lshl_add_u64 v[140:141], v[140:141], 0, s[66:67]
	global_load_dword v111, v[140:141], off nt
	v_lshl_add_u64 v[140:141], v[140:141], 0, s[66:67]
	global_load_dword v112, v[140:141], off nt
	v_lshl_add_u64 v[140:141], v[140:141], 0, s[66:67]
	global_load_dword v113, v[140:141], off nt
	v_lshl_add_u64 v[140:141], v[140:141], 0, s[66:67]
	global_load_dword v114, v[140:141], off nt
	v_lshl_add_u64 v[140:141], v[140:141], 0, s[66:67]
	global_load_dword v115, v[140:141], off nt
	v_lshl_add_u64 v[140:141], v[140:141], 0, s[66:67]
	global_load_dword v116, v[140:141], off nt
	v_lshl_add_u64 v[140:141], v[140:141], 0, s[66:67]
	global_load_dword v117, v[140:141], off nt
	v_lshl_add_u64 v[140:141], v[140:141], 0, s[66:67]
	global_load_dword v118, v[140:141], off nt
	v_lshl_add_u64 v[140:141], v[140:141], 0, s[66:67]
	global_load_dword v119, v[140:141], off nt
	v_lshl_add_u64 v[140:141], v[140:141], 0, s[66:67]
	global_load_dword v120, v[140:141], off nt
	v_lshl_add_u64 v[140:141], v[140:141], 0, s[66:67]
	global_load_dword v121, v[140:141], off nt
	v_lshl_add_u64 v[140:141], v[140:141], 0, s[66:67]
	global_load_dword v122, v[140:141], off nt
	v_lshl_add_u64 v[140:141], v[140:141], 0, s[66:67]
	global_load_dword v123, v[140:141], off nt
	v_lshl_add_u64 v[140:141], v[140:141], 0, s[66:67]
	global_load_dword v124, v[140:141], off nt
	v_lshl_add_u64 v[140:141], v[140:141], 0, s[66:67]
	global_load_dword v125, v[140:141], off nt
	v_lshl_add_u64 v[140:141], v[140:141], 0, s[66:67]
	global_load_dword v126, v[140:141], off nt
	v_lshl_add_u64 v[140:141], v[140:141], 0, s[66:67]
	global_load_dword v127, v[140:141], off nt
	v_lshl_add_u64 v[140:141], v[140:141], 0, s[66:67]
	global_load_dword v128, v[140:141], off nt
	v_lshl_add_u64 v[140:141], v[140:141], 0, s[66:67]
	global_load_dword v129, v[140:141], off nt
	v_lshl_add_u64 v[140:141], v[140:141], 0, s[66:67]
	global_load_dword v130, v[140:141], off nt
	v_lshl_add_u64 v[140:141], v[140:141], 0, s[66:67]
	global_load_dword v131, v[140:141], off nt
	s_waitcnt vmcnt(28)
	ds_write_b32 v142, v100
	ds_write_b32 v142, v101 offset:264
	ds_write_b32 v142, v102 offset:528
	ds_write_b32 v142, v103 offset:792
	s_waitcnt vmcnt(24)
	ds_write_b32 v142, v104 offset:1056
	ds_write_b32 v142, v105 offset:1320
	ds_write_b32 v142, v106 offset:1584
	ds_write_b32 v142, v107 offset:1848
	s_waitcnt vmcnt(20)
	ds_write_b32 v142, v108 offset:2112
	ds_write_b32 v142, v109 offset:2376
	ds_write_b32 v142, v110 offset:2640
	ds_write_b32 v142, v111 offset:2904
	s_waitcnt vmcnt(16)
	ds_write_b32 v142, v112 offset:3168
	ds_write_b32 v142, v113 offset:3432
	ds_write_b32 v142, v114 offset:3696
	ds_write_b32 v142, v115 offset:3960
	s_waitcnt vmcnt(12)
	ds_write_b32 v142, v116 offset:4224
	ds_write_b32 v142, v117 offset:4488
	ds_write_b32 v142, v118 offset:4752
	ds_write_b32 v142, v119 offset:5016
	s_waitcnt vmcnt(8)
	ds_write_b32 v142, v120 offset:5280
	ds_write_b32 v142, v121 offset:5544
	ds_write_b32 v142, v122 offset:5808
	ds_write_b32 v142, v123 offset:6072
	s_waitcnt vmcnt(4)
	ds_write_b32 v142, v124 offset:6336
	ds_write_b32 v142, v125 offset:6600
	ds_write_b32 v142, v126 offset:6864
	ds_write_b32 v142, v127 offset:7128
	s_waitcnt vmcnt(0)
	ds_write_b32 v142, v128 offset:7392
	ds_write_b32 v142, v129 offset:7656
	ds_write_b32 v142, v130 offset:7920
	ds_write_b32 v142, v131 offset:8184
	s_waitcnt lgkmcnt(0)
	ds_read2_b32 v[2:3], v63 offset1:33
	v_add_u32_e32 v16, 0x800, v63
	v_add_u32_e32 v18, 0x400, v63
	v_add_u32_e32 v19, 0xc00, v63
	ds_read2_b32 v[4:5], v16 offset0:16 offset1:49
	ds_read2_b32 v[6:7], v63 offset0:66 offset1:99
	ds_read2_b32 v[8:9], v16 offset0:82 offset1:115
	ds_read2_b32 v[10:11], v63 offset0:132 offset1:165
	ds_read2_b32 v[12:13], v16 offset0:148 offset1:181
	ds_read2_b32 v[14:15], v63 offset0:198 offset1:231
	ds_read2_b32 v[16:17], v16 offset0:214 offset1:247
	ds_read2_b32 v[26:27], v18 offset0:8 offset1:41
	ds_read2_b32 v[28:29], v19 offset0:24 offset1:57
	ds_read2_b32 v[30:31], v18 offset0:74 offset1:107
	ds_read2_b32 v[32:33], v19 offset0:90 offset1:123
	ds_read2_b32 v[80:81], v18 offset0:140 offset1:173
	ds_read2_b32 v[82:83], v19 offset0:156 offset1:189
	ds_read2_b32 v[84:85], v18 offset0:206 offset1:239
	ds_read2_b32 v[86:87], v19 offset0:222 offset1:255
	s_waitcnt lgkmcnt(14)
	v_max_f32_e64 v18, |v4|, |v4|
	v_max_f32_e64 v19, |v2|, |v2|
	v_max_f32_e32 v18, v19, v18
	v_max_f32_e64 v19, |v5|, |v5|
	v_max_f32_e64 v20, |v3|, |v3|
	v_max_f32_e32 v19, v20, v19
	v_max3_f32 v18, v18, 0, v19
	s_waitcnt lgkmcnt(12)
	v_max_f32_e64 v19, |v8|, |v8|
	v_max_f32_e64 v20, |v6|, |v6|
	v_max_f32_e32 v19, v20, v19
	v_max_f32_e64 v20, |v9|, |v9|
	v_max_f32_e64 v21, |v7|, |v7|
	v_max_f32_e32 v20, v21, v20
	v_max3_f32 v18, v18, v19, v20
	s_waitcnt lgkmcnt(10)
	v_max_f32_e64 v19, |v12|, |v12|
	v_max_f32_e64 v20, |v10|, |v10|
	v_max_f32_e32 v19, v20, v19
	v_max_f32_e64 v20, |v13|, |v13|
	v_max_f32_e64 v21, |v11|, |v11|
	v_max_f32_e32 v20, v21, v20
	v_max3_f32 v18, v18, v19, v20
	s_waitcnt lgkmcnt(8)
	v_max_f32_e64 v19, |v16|, |v16|
	v_max_f32_e64 v20, |v14|, |v14|
	v_max_f32_e32 v19, v20, v19
	v_max_f32_e64 v20, |v17|, |v17|
	v_max_f32_e64 v21, |v15|, |v15|
	v_max_f32_e32 v20, v21, v20
	v_max3_f32 v18, v18, v19, v20
	s_waitcnt lgkmcnt(6)
	v_max_f32_e64 v19, |v28|, |v28|
	v_max_f32_e64 v20, |v26|, |v26|
	v_max_f32_e32 v19, v20, v19
	v_max_f32_e64 v20, |v29|, |v29|
	v_max_f32_e64 v21, |v27|, |v27|
	v_max_f32_e32 v20, v21, v20
	v_max3_f32 v18, v18, v19, v20
	s_waitcnt lgkmcnt(4)
	v_max_f32_e64 v19, |v32|, |v32|
	v_max_f32_e64 v20, |v30|, |v30|
	v_max_f32_e32 v19, v20, v19
	v_max_f32_e64 v20, |v33|, |v33|
	v_max_f32_e64 v21, |v31|, |v31|
	v_max_f32_e32 v20, v21, v20
	v_max3_f32 v18, v18, v19, v20
	s_waitcnt lgkmcnt(2)
	v_max_f32_e64 v19, |v82|, |v82|
	v_max_f32_e64 v20, |v80|, |v80|
	v_max_f32_e32 v19, v20, v19
	v_max_f32_e64 v20, |v83|, |v83|
	v_max_f32_e64 v21, |v81|, |v81|
	v_max_f32_e32 v20, v21, v20
	v_max3_f32 v18, v18, v19, v20
	s_waitcnt lgkmcnt(0)
	v_max_f32_e64 v19, |v86|, |v86|
	v_max_f32_e64 v20, |v84|, |v84|
	v_max_f32_e32 v19, v20, v19
	v_max_f32_e64 v20, |v87|, |v87|
	v_max_f32_e64 v21, |v85|, |v85|
	v_max_f32_e32 v20, v21, v20
	v_max3_f32 v18, v18, v19, v20
	v_bfe_u32 v18, v18, 23, 8
	v_max_u32_e32 v34, 3, v18
	v_lshlrev_b32_e32 v18, 23, v34
	v_sub_u32_e32 v61, 0x80000000, v18
	v_mul_f32_e32 v4, v4, v61
	v_med3_f32 v18, v4, s40, v78
	v_mul_f32_e32 v4, v5, v61
	v_mul_f32_e32 v5, v8, v61
	v_med3_f32 v19, v4, s40, v78
	v_mul_f32_e32 v4, v6, v61
	v_med3_f32 v20, v5, s40, v78
	v_mul_f32_e32 v5, v7, v61
	v_mul_f32_e32 v6, v9, v61
	v_mul_f32_e32 v7, v12, v61
	v_mul_f32_e32 v8, v13, v61
	v_mul_f32_e32 v9, v16, v61
	v_med3_f32 v21, v6, s40, v78
	v_mul_f32_e32 v6, v10, v61
	v_med3_f32 v22, v7, s40, v78
	v_mul_f32_e32 v7, v11, v61
	v_med3_f32 v23, v8, s40, v78
	v_mul_f32_e32 v8, v14, v61
	v_med3_f32 v24, v9, s40, v78
	v_mul_f32_e32 v9, v15, v61
	v_mul_f32_e32 v10, v17, v61
	v_mul_f32_e32 v11, v28, v61
	v_mul_f32_e32 v12, v29, v61
	v_mul_f32_e32 v13, v32, v61
	v_mul_f32_e32 v14, v33, v61
	v_mul_f32_e32 v15, v82, v61
	v_mul_f32_e32 v16, v83, v61
	v_mul_f32_e32 v17, v86, v61
	v_mul_f32_e32 v2, v2, v61
	v_mul_f32_e32 v3, v3, v61
	v_med3_f32 v25, v10, s40, v78
	v_mul_f32_e32 v10, v26, v61
	v_med3_f32 v26, v11, s40, v78
	v_mul_f32_e32 v11, v27, v61
	v_med3_f32 v27, v12, s40, v78
	v_mul_f32_e32 v12, v30, v61
	v_med3_f32 v28, v13, s40, v78
	v_mul_f32_e32 v13, v31, v61
	v_med3_f32 v29, v14, s40, v78
	v_mul_f32_e32 v14, v80, v61
	v_med3_f32 v30, v15, s40, v78
	v_mul_f32_e32 v15, v81, v61
	v_med3_f32 v31, v16, s40, v78
	v_mul_f32_e32 v16, v84, v61
	v_med3_f32 v32, v17, s40, v78
	v_mul_f32_e32 v17, v85, v61
	v_mul_f32_e32 v33, v87, v61
	v_med3_f32 v2, v2, s40, v78
	v_med3_f32 v3, v3, s40, v78
	v_med3_f32 v4, v4, s40, v78
	v_med3_f32 v5, v5, s40, v78
	v_med3_f32 v6, v6, s40, v78
	v_med3_f32 v7, v7, s40, v78
	v_med3_f32 v8, v8, s40, v78
	v_med3_f32 v9, v9, s40, v78
	v_med3_f32 v10, v10, s40, v78
	v_med3_f32 v11, v11, s40, v78
	v_med3_f32 v12, v12, s40, v78
	v_med3_f32 v13, v13, s40, v78
	v_med3_f32 v14, v14, s40, v78
	v_med3_f32 v15, v15, s40, v78
	v_med3_f32 v16, v16, s40, v78
	v_med3_f32 v17, v17, s40, v78
	v_med3_f32 v33, v33, s40, v78
	s_and_b32 s11, 0xffff, s11
	v_cvt_scalef32_2xpk16_fp6_f32 v[2:7], v[2:17], v[18:33], 1.0
	v_mov_b32_e32 v32, v6
	v_or_b32_e32 v6, s11, v40
	v_mov_b32_e32 v33, v7
	v_mul_u32_u24_e32 v6, 0x1800, v6
	v_mov_b32_e32 v7, v35
	v_or_b32_e32 v8, s9, v41
	v_lshl_add_u64 v[6:7], s[14:15], 0, v[6:7]
	s_and_b32 s16, s8, 0x7f80
	v_lshrrev_b32_e32 v8, 1, v8
	v_and_b32_e32 v8, 48, v8
	v_mov_b32_e32 v9, v35
	v_lshl_add_u64 v[6:7], v[6:7], 0, s[16:17]
	v_lshl_add_u64 v[6:7], v[6:7], 0, v[8:9]
	v_lshl_add_u64 v[8:9], v[6:7], 0, s[22:23]
	v_add_co_u32_e32 v6, vcc, 0x800000, v6
	v_add_u32_e32 v34, -2, v34
	s_nop 0
	v_addc_co_u32_e32 v7, vcc, 0, v7, vcc
	global_store_dwordx4 v[6:7], v[2:5], off offset:2048
	global_store_dwordx4 v[8:9], v[32:35], off offset:64
	s_waitcnt lgkmcnt(0)
	s_mov_b64 s[8:9], 0

.LBB0_32:
	s_mov_b32 s62, 0x4000
	s_mov_b32 s66, 0x8000
	s_mov_b32 s67, 0
	v_mad_u32_u24 v142, v38, s21, v44
	v_mad_u64_u32 v[140:141], s[64:65], v4, s62, v[2:3]
	global_load_dword v100, v[140:141], off nt
	v_lshl_add_u64 v[140:141], v[140:141], 0, s[66:67]
	global_load_dword v101, v[140:141], off nt
	v_lshl_add_u64 v[140:141], v[140:141], 0, s[66:67]
	global_load_dword v102, v[140:141], off nt
	v_lshl_add_u64 v[140:141], v[140:141], 0, s[66:67]
	global_load_dword v103, v[140:141], off nt
	v_lshl_add_u64 v[140:141], v[140:141], 0, s[66:67]
	global_load_dword v104, v[140:141], off nt
	v_lshl_add_u64 v[140:141], v[140:141], 0, s[66:67]
	global_load_dword v105, v[140:141], off nt
	v_lshl_add_u64 v[140:141], v[140:141], 0, s[66:67]
	global_load_dword v106, v[140:141], off nt
	v_lshl_add_u64 v[140:141], v[140:141], 0, s[66:67]
	global_load_dword v107, v[140:141], off nt
	v_lshl_add_u64 v[140:141], v[140:141], 0, s[66:67]
	global_load_dword v108, v[140:141], off nt
	v_lshl_add_u64 v[140:141], v[140:141], 0, s[66:67]
	global_load_dword v109, v[140:141], off nt
	v_lshl_add_u64 v[140:141], v[140:141], 0, s[66:67]
	global_load_dword v110, v[140:141], off nt
	v_lshl_add_u64 v[140:141], v[140:141], 0, s[66:67]
	global_load_dword v111, v[140:141], off nt
	v_lshl_add_u64 v[140:141], v[140:141], 0, s[66:67]
	global_load_dword v112, v[140:141], off nt
	v_lshl_add_u64 v[140:141], v[140:141], 0, s[66:67]
	global_load_dword v113, v[140:141], off nt
	v_lshl_add_u64 v[140:141], v[140:141], 0, s[66:67]
	global_load_dword v114, v[140:141], off nt
	v_lshl_add_u64 v[140:141], v[140:141], 0, s[66:67]
	global_load_dword v115, v[140:141], off nt
	v_lshl_add_u64 v[140:141], v[140:141], 0, s[66:67]
	global_load_dword v116, v[140:141], off nt
	v_lshl_add_u64 v[140:141], v[140:141], 0, s[66:67]
	global_load_dword v117, v[140:141], off nt
	v_lshl_add_u64 v[140:141], v[140:141], 0, s[66:67]
	global_load_dword v118, v[140:141], off nt
	v_lshl_add_u64 v[140:141], v[140:141], 0, s[66:67]
	global_load_dword v119, v[140:141], off nt
	v_lshl_add_u64 v[140:141], v[140:141], 0, s[66:67]
	global_load_dword v120, v[140:141], off nt
	v_lshl_add_u64 v[140:141], v[140:141], 0, s[66:67]
	global_load_dword v121, v[140:141], off nt
	v_lshl_add_u64 v[140:141], v[140:141], 0, s[66:67]
	global_load_dword v122, v[140:141], off nt
	v_lshl_add_u64 v[140:141], v[140:141], 0, s[66:67]
	global_load_dword v123, v[140:141], off nt
	v_lshl_add_u64 v[140:141], v[140:141], 0, s[66:67]
	global_load_dword v124, v[140:141], off nt
	v_lshl_add_u64 v[140:141], v[140:141], 0, s[66:67]
	global_load_dword v125, v[140:141], off nt
	v_lshl_add_u64 v[140:141], v[140:141], 0, s[66:67]
	global_load_dword v126, v[140:141], off nt
	v_lshl_add_u64 v[140:141], v[140:141], 0, s[66:67]
	global_load_dword v127, v[140:141], off nt
	v_lshl_add_u64 v[140:141], v[140:141], 0, s[66:67]
	global_load_dword v128, v[140:141], off nt
	v_lshl_add_u64 v[140:141], v[140:141], 0, s[66:67]
	global_load_dword v129, v[140:141], off nt
	v_lshl_add_u64 v[140:141], v[140:141], 0, s[66:67]
	global_load_dword v130, v[140:141], off nt
	v_lshl_add_u64 v[140:141], v[140:141], 0, s[66:67]
	global_load_dword v131, v[140:141], off nt
	s_waitcnt vmcnt(28)
	ds_write_b32 v142, v100
	ds_write_b32 v142, v101 offset:264
	ds_write_b32 v142, v102 offset:528
	ds_write_b32 v142, v103 offset:792
	s_waitcnt vmcnt(24)
	ds_write_b32 v142, v104 offset:1056
	ds_write_b32 v142, v105 offset:1320
	ds_write_b32 v142, v106 offset:1584
	ds_write_b32 v142, v107 offset:1848
	s_waitcnt vmcnt(20)
	ds_write_b32 v142, v108 offset:2112
	ds_write_b32 v142, v109 offset:2376
	ds_write_b32 v142, v110 offset:2640
	ds_write_b32 v142, v111 offset:2904
	s_waitcnt vmcnt(16)
	ds_write_b32 v142, v112 offset:3168
	ds_write_b32 v142, v113 offset:3432
	ds_write_b32 v142, v114 offset:3696
	ds_write_b32 v142, v115 offset:3960
	s_waitcnt vmcnt(12)
	ds_write_b32 v142, v116 offset:4224
	ds_write_b32 v142, v117 offset:4488
	ds_write_b32 v142, v118 offset:4752
	ds_write_b32 v142, v119 offset:5016
	s_waitcnt vmcnt(8)
	ds_write_b32 v142, v120 offset:5280
	ds_write_b32 v142, v121 offset:5544
	ds_write_b32 v142, v122 offset:5808
	ds_write_b32 v142, v123 offset:6072
	s_waitcnt vmcnt(4)
	ds_write_b32 v142, v124 offset:6336
	ds_write_b32 v142, v125 offset:6600
	ds_write_b32 v142, v126 offset:6864
	ds_write_b32 v142, v127 offset:7128
	s_waitcnt vmcnt(0)
	ds_write_b32 v142, v128 offset:7392
	ds_write_b32 v142, v129 offset:7656
	ds_write_b32 v142, v130 offset:7920
	ds_write_b32 v142, v131 offset:8184
	s_waitcnt lgkmcnt(0)
	ds_read2_b32 v[6:7], v65 offset1:8
	ds_read2_b32 v[10:11], v65 offset0:33 offset1:41
	ds_read2_b32 v[12:13], v65 offset0:66 offset1:74
	ds_read2_b32 v[14:15], v65 offset0:99 offset1:107
	ds_read2_b32 v[16:17], v65 offset0:132 offset1:140
	ds_read2_b32 v[18:19], v65 offset0:165 offset1:173
	s_waitcnt lgkmcnt(5)
	v_bfe_u32 v2, v6, 16, 1
	v_add3_u32 v2, v6, v2, s41
	s_waitcnt lgkmcnt(4)
	v_bfe_u32 v3, v10, 16, 1
	v_lshrrev_b32_e32 v2, 16, v2
	v_add3_u32 v3, v10, v3, s41
	v_and_or_b32 v2, v3, s42, v2
	s_waitcnt lgkmcnt(3)
	v_bfe_u32 v3, v12, 16, 1
	v_add3_u32 v3, v12, v3, s41
	s_waitcnt lgkmcnt(2)
	v_bfe_u32 v4, v14, 16, 1
	ds_read2_b32 v[20:21], v65 offset0:198 offset1:206
	v_lshrrev_b32_e32 v3, 16, v3
	v_add3_u32 v4, v14, v4, s41
	ds_read2_b32 v[22:23], v65 offset0:231 offset1:239
	v_and_or_b32 v3, v4, s42, v3
	s_waitcnt lgkmcnt(3)
	v_bfe_u32 v4, v16, 16, 1
	v_add3_u32 v4, v16, v4, s41
	s_waitcnt lgkmcnt(2)
	v_bfe_u32 v5, v18, 16, 1
	v_lshrrev_b32_e32 v4, 16, v4
	v_add3_u32 v5, v18, v5, s41
	v_and_or_b32 v4, v5, s42, v4
	s_waitcnt lgkmcnt(1)
	v_bfe_u32 v5, v20, 16, 1
	v_add3_u32 v5, v20, v5, s41
	s_waitcnt lgkmcnt(0)
	v_bfe_u32 v6, v22, 16, 1
	v_lshrrev_b32_e32 v5, 16, v5
	v_add3_u32 v6, v22, v6, s41
	v_and_or_b32 v5, v6, s42, v5
	v_or_b32_e32 v6, s8, v64
	s_lshl_b32 s16, s9, 1
	v_mul_u32_u24_e32 v6, 0xc00, v6
	v_lshl_add_u64 v[8:9], v[48:49], 0, s[16:17]
	v_lshlrev_b32_e32 v34, 1, v6
	v_lshl_add_u64 v[24:25], v[8:9], 0, v[34:35]
	global_store_dwordx4 v[24:25], v[2:5], off
	v_bfe_u32 v6, v23, 16, 1
	v_add3_u32 v6, v23, v6, s41
	v_bfe_u32 v2, v7, 16, 1
	v_add3_u32 v2, v7, v2, s41
	v_bfe_u32 v3, v11, 16, 1
	v_lshrrev_b32_e32 v2, 16, v2
	v_add3_u32 v3, v11, v3, s41
	v_and_or_b32 v2, v3, s42, v2
	v_bfe_u32 v3, v13, 16, 1
	v_add3_u32 v3, v13, v3, s41
	v_bfe_u32 v4, v15, 16, 1
	v_lshrrev_b32_e32 v3, 16, v3
	v_add3_u32 v4, v15, v4, s41
	v_and_or_b32 v3, v4, s42, v3
	v_bfe_u32 v4, v17, 16, 1
	v_add3_u32 v4, v17, v4, s41
	v_bfe_u32 v5, v19, 16, 1
	v_lshrrev_b32_e32 v4, 16, v4
	v_add3_u32 v5, v19, v5, s41
	v_and_or_b32 v4, v5, s42, v4
	v_bfe_u32 v5, v21, 16, 1
	v_add3_u32 v5, v21, v5, s41
	v_lshrrev_b32_e32 v5, 16, v5
	v_and_or_b32 v5, v6, s42, v5
	v_or_b32_e32 v6, s8, v66
	v_mul_u32_u24_e32 v10, 0xc00, v6
	v_lshlrev_b32_e32 v34, 1, v10
	ds_read2_b32 v[6:7], v65 offset0:16 offset1:24
	v_lshl_add_u64 v[10:11], v[8:9], 0, v[34:35]
	global_store_dwordx4 v[10:11], v[2:5], off
	ds_read2_b32 v[10:11], v65 offset0:49 offset1:57
	ds_read2_b32 v[12:13], v65 offset0:82 offset1:90
	ds_read2_b32 v[14:15], v65 offset0:115 offset1:123
	s_waitcnt lgkmcnt(3)
	v_bfe_u32 v2, v6, 16, 1
	v_add3_u32 v2, v6, v2, s41
	s_waitcnt lgkmcnt(2)
	v_bfe_u32 v3, v10, 16, 1
	ds_read2_b32 v[16:17], v65 offset0:148 offset1:156
	v_lshrrev_b32_e32 v2, 16, v2
	v_add3_u32 v3, v10, v3, s41
	ds_read2_b32 v[18:19], v65 offset0:181 offset1:189
	v_and_or_b32 v2, v3, s42, v2
	s_waitcnt lgkmcnt(3)
	v_bfe_u32 v3, v12, 16, 1
	v_add3_u32 v3, v12, v3, s41
	s_waitcnt lgkmcnt(2)
	v_bfe_u32 v4, v14, 16, 1
	ds_read2_b32 v[20:21], v65 offset0:214 offset1:222
	v_lshrrev_b32_e32 v3, 16, v3
	v_add3_u32 v4, v14, v4, s41
	ds_read2_b32 v[22:23], v65 offset0:247 offset1:255
	v_and_or_b32 v3, v4, s42, v3
	s_waitcnt lgkmcnt(3)
	v_bfe_u32 v4, v16, 16, 1
	v_add3_u32 v4, v16, v4, s41
	s_waitcnt lgkmcnt(2)
	v_bfe_u32 v5, v18, 16, 1
	v_lshrrev_b32_e32 v4, 16, v4
	v_add3_u32 v5, v18, v5, s41
	v_and_or_b32 v4, v5, s42, v4
	s_waitcnt lgkmcnt(1)
	v_bfe_u32 v5, v20, 16, 1
	v_add3_u32 v5, v20, v5, s41
	s_waitcnt lgkmcnt(0)
	v_bfe_u32 v6, v22, 16, 1
	v_lshrrev_b32_e32 v5, 16, v5
	v_add3_u32 v6, v22, v6, s41
	v_and_or_b32 v5, v6, s42, v5
	v_or_b32_e32 v6, s8, v67
	v_mul_u32_u24_e32 v6, 0xc00, v6
	v_lshlrev_b32_e32 v34, 1, v6
	v_lshl_add_u64 v[24:25], v[8:9], 0, v[34:35]
	global_store_dwordx4 v[24:25], v[2:5], off
	v_bfe_u32 v6, v23, 16, 1
	v_add3_u32 v6, v23, v6, s41
	v_bfe_u32 v2, v7, 16, 1
	v_add3_u32 v2, v7, v2, s41
	v_bfe_u32 v3, v11, 16, 1
	v_lshrrev_b32_e32 v2, 16, v2
	v_add3_u32 v3, v11, v3, s41
	v_and_or_b32 v2, v3, s42, v2
	v_bfe_u32 v3, v13, 16, 1
	v_add3_u32 v3, v13, v3, s41
	v_bfe_u32 v4, v15, 16, 1
	v_lshrrev_b32_e32 v3, 16, v3
	v_add3_u32 v4, v15, v4, s41
	v_and_or_b32 v3, v4, s42, v3
	v_bfe_u32 v4, v17, 16, 1
	v_add3_u32 v4, v17, v4, s41
	v_bfe_u32 v5, v19, 16, 1
	v_lshrrev_b32_e32 v4, 16, v4
	v_add3_u32 v5, v19, v5, s41
	v_and_or_b32 v4, v5, s42, v4
	v_bfe_u32 v5, v21, 16, 1
	v_add3_u32 v5, v21, v5, s41
	v_lshrrev_b32_e32 v5, 16, v5
	v_and_or_b32 v5, v6, s42, v5
	v_or_b32_e32 v6, s8, v68
	v_mul_u32_u24_e32 v6, 0xc00, v6
	v_lshlrev_b32_e32 v34, 1, v6
	v_lshl_add_u64 v[6:7], v[8:9], 0, v[34:35]
	global_store_dwordx4 v[6:7], v[2:5], off
	s_waitcnt lgkmcnt(0)

.LBB0_80:
	s_mov_b32 s62, s46
	s_lshl_b32 s66, s46, 1
	s_mov_b32 s67, 0
	v_mad_u32_u24 v142, v38, s21, v44
	v_mad_u64_u32 v[140:141], s[64:65], v2, s62, v[4:5]
	global_load_dword v100, v[140:141], off nt
	v_lshl_add_u64 v[140:141], v[140:141], 0, s[66:67]
	global_load_dword v101, v[140:141], off nt
	v_lshl_add_u64 v[140:141], v[140:141], 0, s[66:67]
	global_load_dword v102, v[140:141], off nt
	v_lshl_add_u64 v[140:141], v[140:141], 0, s[66:67]
	global_load_dword v103, v[140:141], off nt
	v_lshl_add_u64 v[140:141], v[140:141], 0, s[66:67]
	global_load_dword v104, v[140:141], off nt
	v_lshl_add_u64 v[140:141], v[140:141], 0, s[66:67]
	global_load_dword v105, v[140:141], off nt
	v_lshl_add_u64 v[140:141], v[140:141], 0, s[66:67]
	global_load_dword v106, v[140:141], off nt
	v_lshl_add_u64 v[140:141], v[140:141], 0, s[66:67]
	global_load_dword v107, v[140:141], off nt
	v_lshl_add_u64 v[140:141], v[140:141], 0, s[66:67]
	global_load_dword v108, v[140:141], off nt
	v_lshl_add_u64 v[140:141], v[140:141], 0, s[66:67]
	global_load_dword v109, v[140:141], off nt
	v_lshl_add_u64 v[140:141], v[140:141], 0, s[66:67]
	global_load_dword v110, v[140:141], off nt
	v_lshl_add_u64 v[140:141], v[140:141], 0, s[66:67]
	global_load_dword v111, v[140:141], off nt
	v_lshl_add_u64 v[140:141], v[140:141], 0, s[66:67]
	global_load_dword v112, v[140:141], off nt
	v_lshl_add_u64 v[140:141], v[140:141], 0, s[66:67]
	global_load_dword v113, v[140:141], off nt
	v_lshl_add_u64 v[140:141], v[140:141], 0, s[66:67]
	global_load_dword v114, v[140:141], off nt
	v_lshl_add_u64 v[140:141], v[140:141], 0, s[66:67]
	global_load_dword v115, v[140:141], off nt
	v_lshl_add_u64 v[140:141], v[140:141], 0, s[66:67]
	global_load_dword v116, v[140:141], off nt
	v_lshl_add_u64 v[140:141], v[140:141], 0, s[66:67]
	global_load_dword v117, v[140:141], off nt
	v_lshl_add_u64 v[140:141], v[140:141], 0, s[66:67]
	global_load_dword v118, v[140:141], off nt
	v_lshl_add_u64 v[140:141], v[140:141], 0, s[66:67]
	global_load_dword v119, v[140:141], off nt
	v_lshl_add_u64 v[140:141], v[140:141], 0, s[66:67]
	global_load_dword v120, v[140:141], off nt
	v_lshl_add_u64 v[140:141], v[140:141], 0, s[66:67]
	global_load_dword v121, v[140:141], off nt
	v_lshl_add_u64 v[140:141], v[140:141], 0, s[66:67]
	global_load_dword v122, v[140:141], off nt
	v_lshl_add_u64 v[140:141], v[140:141], 0, s[66:67]
	global_load_dword v123, v[140:141], off nt
	v_lshl_add_u64 v[140:141], v[140:141], 0, s[66:67]
	global_load_dword v124, v[140:141], off nt
	v_lshl_add_u64 v[140:141], v[140:141], 0, s[66:67]
	global_load_dword v125, v[140:141], off nt
	v_lshl_add_u64 v[140:141], v[140:141], 0, s[66:67]
	global_load_dword v126, v[140:141], off nt
	v_lshl_add_u64 v[140:141], v[140:141], 0, s[66:67]
	global_load_dword v127, v[140:141], off nt
	v_lshl_add_u64 v[140:141], v[140:141], 0, s[66:67]
	global_load_dword v128, v[140:141], off nt
	v_lshl_add_u64 v[140:141], v[140:141], 0, s[66:67]
	global_load_dword v129, v[140:141], off nt
	v_lshl_add_u64 v[140:141], v[140:141], 0, s[66:67]
	global_load_dword v130, v[140:141], off nt
	v_lshl_add_u64 v[140:141], v[140:141], 0, s[66:67]
	global_load_dword v131, v[140:141], off nt
	s_waitcnt vmcnt(28)
	v_pk_mul_f32 v[100:101], v[100:101], s[24:25] op_sel_hi:[1,0]
	v_pk_mul_f32 v[102:103], v[102:103], s[24:25] op_sel_hi:[1,0]
	ds_write_b32 v142, v100
	ds_write_b32 v142, v101 offset:264
	ds_write_b32 v142, v102 offset:528
	ds_write_b32 v142, v103 offset:792
	s_waitcnt vmcnt(24)
	v_pk_mul_f32 v[104:105], v[104:105], s[24:25] op_sel_hi:[1,0]
	v_pk_mul_f32 v[106:107], v[106:107], s[24:25] op_sel_hi:[1,0]
	ds_write_b32 v142, v104 offset:1056
	ds_write_b32 v142, v105 offset:1320
	ds_write_b32 v142, v106 offset:1584
	ds_write_b32 v142, v107 offset:1848
	s_waitcnt vmcnt(20)
	v_pk_mul_f32 v[108:109], v[108:109], s[24:25] op_sel_hi:[1,0]
	v_pk_mul_f32 v[110:111], v[110:111], s[24:25] op_sel_hi:[1,0]
	ds_write_b32 v142, v108 offset:2112
	ds_write_b32 v142, v109 offset:2376
	ds_write_b32 v142, v110 offset:2640
	ds_write_b32 v142, v111 offset:2904
	s_waitcnt vmcnt(16)
	v_pk_mul_f32 v[112:113], v[112:113], s[24:25] op_sel_hi:[1,0]
	v_pk_mul_f32 v[114:115], v[114:115], s[24:25] op_sel_hi:[1,0]
	ds_write_b32 v142, v112 offset:3168
	ds_write_b32 v142, v113 offset:3432
	ds_write_b32 v142, v114 offset:3696
	ds_write_b32 v142, v115 offset:3960
	s_waitcnt vmcnt(12)
	v_pk_mul_f32 v[116:117], v[116:117], s[24:25] op_sel_hi:[1,0]
	v_pk_mul_f32 v[118:119], v[118:119], s[24:25] op_sel_hi:[1,0]
	ds_write_b32 v142, v116 offset:4224
	ds_write_b32 v142, v117 offset:4488
	ds_write_b32 v142, v118 offset:4752
	ds_write_b32 v142, v119 offset:5016
	s_waitcnt vmcnt(8)
	v_pk_mul_f32 v[120:121], v[120:121], s[24:25] op_sel_hi:[1,0]
	v_pk_mul_f32 v[122:123], v[122:123], s[24:25] op_sel_hi:[1,0]
	ds_write_b32 v142, v120 offset:5280
	ds_write_b32 v142, v121 offset:5544
	ds_write_b32 v142, v122 offset:5808
	ds_write_b32 v142, v123 offset:6072
	s_waitcnt vmcnt(4)
	v_pk_mul_f32 v[124:125], v[124:125], s[24:25] op_sel_hi:[1,0]
	v_pk_mul_f32 v[126:127], v[126:127], s[24:25] op_sel_hi:[1,0]
	ds_write_b32 v142, v124 offset:6336
	ds_write_b32 v142, v125 offset:6600
	ds_write_b32 v142, v126 offset:6864
	ds_write_b32 v142, v127 offset:7128
	s_waitcnt vmcnt(0)
	v_pk_mul_f32 v[128:129], v[128:129], s[24:25] op_sel_hi:[1,0]
	v_pk_mul_f32 v[130:131], v[130:131], s[24:25] op_sel_hi:[1,0]
	ds_write_b32 v142, v128 offset:7392
	ds_write_b32 v142, v129 offset:7656
	ds_write_b32 v142, v130 offset:7920
	ds_write_b32 v142, v131 offset:8184
	s_waitcnt lgkmcnt(0)
	ds_read2_b32 v[8:9], v59 offset1:16
	ds_read2_b32 v[10:11], v59 offset0:33 offset1:49
	ds_read2_b32 v[12:13], v59 offset0:66 offset1:82
	ds_read2_b32 v[14:15], v59 offset0:99 offset1:115
	ds_read2_b32 v[18:19], v59 offset0:132 offset1:148
	ds_read2_b32 v[20:21], v59 offset0:165 offset1:181
	ds_read2_b32 v[22:23], v59 offset0:198 offset1:214
	ds_read2_b32 v[24:25], v59 offset0:231 offset1:247
	s_waitcnt lgkmcnt(7)
	v_max_f32_e32 v4, v8, v8
	s_waitcnt lgkmcnt(6)
	v_max_f32_e32 v5, v10, v10
	v_med3_f32 v8, v4, s39, v77
	v_med3_f32 v5, v5, s39, v77
	v_mov_b32_e32 v4, v35
	v_cvt_pk_fp8_f32 v4, v8, v5
	s_waitcnt lgkmcnt(5)
	v_max_f32_e32 v6, v12, v12
	s_waitcnt lgkmcnt(4)
	v_max_f32_e32 v7, v14, v14
	v_med3_f32 v6, v6, s39, v77
	v_med3_f32 v7, v7, s39, v77
	v_cvt_pk_fp8_f32 v4, v6, v7 op_sel:[0,0,1]
	s_waitcnt lgkmcnt(3)
	v_max_f32_e32 v5, v18, v18
	s_waitcnt lgkmcnt(2)
	v_max_f32_e32 v6, v20, v20
	v_med3_f32 v10, v5, s39, v77
	v_med3_f32 v6, v6, s39, v77
	v_mov_b32_e32 v5, v35
	v_cvt_pk_fp8_f32 v5, v10, v6
	v_add_u32_e32 v10, 0x400, v59
	ds_read2_b32 v[26:27], v10 offset0:8 offset1:24
	ds_read2_b32 v[28:29], v10 offset0:41 offset1:57
	ds_read2_b32 v[30:31], v10 offset0:74 offset1:90
	ds_read2_b32 v[32:33], v10 offset0:107 offset1:123
	s_waitcnt lgkmcnt(5)
	v_max_f32_e32 v7, v22, v22
	s_waitcnt lgkmcnt(4)
	v_max_f32_e32 v8, v24, v24
	v_med3_f32 v7, v7, s39, v77
	v_med3_f32 v8, v8, s39, v77
	v_cvt_pk_fp8_f32 v5, v7, v8 op_sel:[0,0,1]
	s_waitcnt lgkmcnt(3)
	v_max_f32_e32 v6, v26, v26
	s_waitcnt lgkmcnt(2)
	v_max_f32_e32 v7, v28, v28
	v_med3_f32 v14, v6, s39, v77
	v_med3_f32 v7, v7, s39, v77
	v_mov_b32_e32 v6, v35
	v_cvt_pk_fp8_f32 v6, v14, v7
	ds_read2_b32 v[80:81], v10 offset0:140 offset1:156
	ds_read2_b32 v[82:83], v10 offset0:173 offset1:189
	ds_read2_b32 v[84:85], v10 offset0:206 offset1:222
	s_waitcnt lgkmcnt(4)
	v_max_f32_e32 v8, v30, v30
	s_waitcnt lgkmcnt(3)
	v_max_f32_e32 v12, v32, v32
	v_med3_f32 v8, v8, s39, v77
	v_med3_f32 v7, v12, s39, v77
	ds_read2_b32 v[86:87], v10 offset0:239 offset1:255
	v_cvt_pk_fp8_f32 v6, v8, v7 op_sel:[0,0,1]
	s_waitcnt lgkmcnt(3)
	v_max_f32_e32 v7, v80, v80
	s_waitcnt lgkmcnt(2)
	v_max_f32_e32 v8, v82, v82
	v_med3_f32 v10, v7, s39, v77
	v_med3_f32 v8, v8, s39, v77
	v_mov_b32_e32 v7, v35
	v_cvt_pk_fp8_f32 v7, v10, v8
	s_waitcnt lgkmcnt(1)
	v_max_f32_e32 v12, v84, v84
	s_waitcnt lgkmcnt(0)
	v_max_f32_e32 v8, v86, v86
	v_med3_f32 v10, v12, s39, v77
	v_med3_f32 v8, v8, s39, v77
	v_cvt_pk_fp8_f32 v7, v10, v8 op_sel:[0,0,1]
	s_ashr_i32 s9, s8, 31
	v_or_b32_e32 v34, s6, v45
	v_lshl_add_u64 v[16:17], v[54:55], 0, s[8:9]
	v_lshlrev_b64 v[88:89], 12, v[34:35]
	v_lshl_add_u64 v[88:89], v[16:17], 0, v[88:89]
	global_store_dwordx4 v[88:89], v[4:7], off
	v_or_b32_e32 v34, s6, v62
	s_mov_b64 s[26:27], 0
	v_max_f32_e32 v4, v9, v9
	v_max_f32_e32 v5, v11, v11
	v_med3_f32 v7, v4, s39, v77
	v_med3_f32 v5, v5, s39, v77
	v_mov_b32_e32 v4, v35
	v_cvt_pk_fp8_f32 v4, v7, v5
	v_max_f32_e32 v6, v13, v13
	v_max_f32_e32 v5, v15, v15
	v_med3_f32 v6, v6, s39, v77
	v_med3_f32 v5, v5, s39, v77
	v_cvt_pk_fp8_f32 v4, v6, v5 op_sel:[0,0,1]
	v_max_f32_e32 v5, v19, v19
	v_max_f32_e32 v6, v21, v21
	v_med3_f32 v8, v5, s39, v77
	v_med3_f32 v6, v6, s39, v77
	v_mov_b32_e32 v5, v35
	v_cvt_pk_fp8_f32 v5, v8, v6
	v_max_f32_e32 v7, v23, v23
	v_max_f32_e32 v6, v25, v25
	v_med3_f32 v7, v7, s39, v77
	v_med3_f32 v6, v6, s39, v77
	v_cvt_pk_fp8_f32 v5, v7, v6 op_sel:[0,0,1]
	v_max_f32_e32 v6, v27, v27
	v_max_f32_e32 v7, v29, v29
	v_med3_f32 v9, v6, s39, v77
	v_med3_f32 v7, v7, s39, v77
	v_mov_b32_e32 v6, v35
	v_cvt_pk_fp8_f32 v6, v9, v7
	v_max_f32_e32 v8, v31, v31
	v_max_f32_e32 v7, v33, v33
	v_med3_f32 v8, v8, s39, v77
	v_med3_f32 v7, v7, s39, v77
	v_cvt_pk_fp8_f32 v6, v8, v7 op_sel:[0,0,1]
	v_max_f32_e32 v7, v81, v81
	v_max_f32_e32 v8, v83, v83
	v_med3_f32 v10, v7, s39, v77
	v_med3_f32 v8, v8, s39, v77
	v_mov_b32_e32 v7, v35
	v_cvt_pk_fp8_f32 v7, v10, v8
	v_max_f32_e32 v9, v85, v85
	v_max_f32_e32 v8, v87, v87
	v_med3_f32 v9, v9, s39, v77
	v_med3_f32 v8, v8, s39, v77
	v_cvt_pk_fp8_f32 v7, v9, v8 op_sel:[0,0,1]
	v_lshlrev_b64 v[8:9], 12, v[34:35]
	v_lshl_add_u64 v[8:9], v[16:17], 0, v[8:9]
	global_store_dwordx4 v[8:9], v[4:7], off
	s_waitcnt lgkmcnt(0)

.LBB0_84:
	s_mov_b32 s62, s46
	s_lshl_b32 s66, s46, 1
	s_mov_b32 s67, 0
	v_mad_u32_u24 v142, v38, s21, v44
	v_mad_u64_u32 v[140:141], s[64:65], v2, s62, v[4:5]
	global_load_dword v100, v[140:141], off nt
	v_lshl_add_u64 v[140:141], v[140:141], 0, s[66:67]
	global_load_dword v101, v[140:141], off nt
	v_lshl_add_u64 v[140:141], v[140:141], 0, s[66:67]
	global_load_dword v102, v[140:141], off nt
	v_lshl_add_u64 v[140:141], v[140:141], 0, s[66:67]
	global_load_dword v103, v[140:141], off nt
	v_lshl_add_u64 v[140:141], v[140:141], 0, s[66:67]
	global_load_dword v104, v[140:141], off nt
	v_lshl_add_u64 v[140:141], v[140:141], 0, s[66:67]
	global_load_dword v105, v[140:141], off nt
	v_lshl_add_u64 v[140:141], v[140:141], 0, s[66:67]
	global_load_dword v106, v[140:141], off nt
	v_lshl_add_u64 v[140:141], v[140:141], 0, s[66:67]
	global_load_dword v107, v[140:141], off nt
	v_lshl_add_u64 v[140:141], v[140:141], 0, s[66:67]
	global_load_dword v108, v[140:141], off nt
	v_lshl_add_u64 v[140:141], v[140:141], 0, s[66:67]
	global_load_dword v109, v[140:141], off nt
	v_lshl_add_u64 v[140:141], v[140:141], 0, s[66:67]
	global_load_dword v110, v[140:141], off nt
	v_lshl_add_u64 v[140:141], v[140:141], 0, s[66:67]
	global_load_dword v111, v[140:141], off nt
	v_lshl_add_u64 v[140:141], v[140:141], 0, s[66:67]
	global_load_dword v112, v[140:141], off nt
	v_lshl_add_u64 v[140:141], v[140:141], 0, s[66:67]
	global_load_dword v113, v[140:141], off nt
	v_lshl_add_u64 v[140:141], v[140:141], 0, s[66:67]
	global_load_dword v114, v[140:141], off nt
	v_lshl_add_u64 v[140:141], v[140:141], 0, s[66:67]
	global_load_dword v115, v[140:141], off nt
	v_lshl_add_u64 v[140:141], v[140:141], 0, s[66:67]
	global_load_dword v116, v[140:141], off nt
	v_lshl_add_u64 v[140:141], v[140:141], 0, s[66:67]
	global_load_dword v117, v[140:141], off nt
	v_lshl_add_u64 v[140:141], v[140:141], 0, s[66:67]
	global_load_dword v118, v[140:141], off nt
	v_lshl_add_u64 v[140:141], v[140:141], 0, s[66:67]
	global_load_dword v119, v[140:141], off nt
	v_lshl_add_u64 v[140:141], v[140:141], 0, s[66:67]
	global_load_dword v120, v[140:141], off nt
	v_lshl_add_u64 v[140:141], v[140:141], 0, s[66:67]
	global_load_dword v121, v[140:141], off nt
	v_lshl_add_u64 v[140:141], v[140:141], 0, s[66:67]
	global_load_dword v122, v[140:141], off nt
	v_lshl_add_u64 v[140:141], v[140:141], 0, s[66:67]
	global_load_dword v123, v[140:141], off nt
	v_lshl_add_u64 v[140:141], v[140:141], 0, s[66:67]
	global_load_dword v124, v[140:141], off nt
	v_lshl_add_u64 v[140:141], v[140:141], 0, s[66:67]
	global_load_dword v125, v[140:141], off nt
	v_lshl_add_u64 v[140:141], v[140:141], 0, s[66:67]
	global_load_dword v126, v[140:141], off nt
	v_lshl_add_u64 v[140:141], v[140:141], 0, s[66:67]
	global_load_dword v127, v[140:141], off nt
	v_lshl_add_u64 v[140:141], v[140:141], 0, s[66:67]
	global_load_dword v128, v[140:141], off nt
	v_lshl_add_u64 v[140:141], v[140:141], 0, s[66:67]
	global_load_dword v129, v[140:141], off nt
	v_lshl_add_u64 v[140:141], v[140:141], 0, s[66:67]
	global_load_dword v130, v[140:141], off nt
	v_lshl_add_u64 v[140:141], v[140:141], 0, s[66:67]
	global_load_dword v131, v[140:141], off nt
	s_waitcnt vmcnt(28)
	ds_write_b32 v142, v100
	ds_write_b32 v142, v101 offset:264
	ds_write_b32 v142, v102 offset:528
	ds_write_b32 v142, v103 offset:792
	s_waitcnt vmcnt(24)
	ds_write_b32 v142, v104 offset:1056
	ds_write_b32 v142, v105 offset:1320
	ds_write_b32 v142, v106 offset:1584
	ds_write_b32 v142, v107 offset:1848
	s_waitcnt vmcnt(20)
	ds_write_b32 v142, v108 offset:2112
	ds_write_b32 v142, v109 offset:2376
	ds_write_b32 v142, v110 offset:2640
	ds_write_b32 v142, v111 offset:2904
	s_waitcnt vmcnt(16)
	ds_write_b32 v142, v112 offset:3168
	ds_write_b32 v142, v113 offset:3432
	ds_write_b32 v142, v114 offset:3696
	ds_write_b32 v142, v115 offset:3960
	s_waitcnt vmcnt(12)
	ds_write_b32 v142, v116 offset:4224
	ds_write_b32 v142, v117 offset:4488
	ds_write_b32 v142, v118 offset:4752
	ds_write_b32 v142, v119 offset:5016
	s_waitcnt vmcnt(8)
	ds_write_b32 v142, v120 offset:5280
	ds_write_b32 v142, v121 offset:5544
	ds_write_b32 v142, v122 offset:5808
	ds_write_b32 v142, v123 offset:6072
	s_waitcnt vmcnt(4)
	ds_write_b32 v142, v124 offset:6336
	ds_write_b32 v142, v125 offset:6600
	ds_write_b32 v142, v126 offset:6864
	ds_write_b32 v142, v127 offset:7128
	s_waitcnt vmcnt(0)
	ds_write_b32 v142, v128 offset:7392
	ds_write_b32 v142, v129 offset:7656
	ds_write_b32 v142, v130 offset:7920
	ds_write_b32 v142, v131 offset:8184
	s_waitcnt lgkmcnt(0)
	ds_read2_b32 v[6:7], v65 offset1:8
	ds_read2_b32 v[10:11], v65 offset0:33 offset1:41
	ds_read2_b32 v[12:13], v65 offset0:66 offset1:74
	ds_read2_b32 v[14:15], v65 offset0:99 offset1:107
	ds_read2_b32 v[16:17], v65 offset0:132 offset1:140
	ds_read2_b32 v[18:19], v65 offset0:165 offset1:173
	s_waitcnt lgkmcnt(5)
	v_bfe_u32 v2, v6, 16, 1
	v_add3_u32 v2, v6, v2, s41
	s_waitcnt lgkmcnt(4)
	v_bfe_u32 v3, v10, 16, 1
	v_lshrrev_b32_e32 v2, 16, v2
	v_add3_u32 v3, v10, v3, s41
	v_and_or_b32 v2, v3, s42, v2
	s_waitcnt lgkmcnt(3)
	v_bfe_u32 v3, v12, 16, 1
	v_add3_u32 v3, v12, v3, s41
	s_waitcnt lgkmcnt(2)
	v_bfe_u32 v4, v14, 16, 1
	ds_read2_b32 v[20:21], v65 offset0:198 offset1:206
	v_lshrrev_b32_e32 v3, 16, v3
	v_add3_u32 v4, v14, v4, s41
	ds_read2_b32 v[22:23], v65 offset0:231 offset1:239
	v_and_or_b32 v3, v4, s42, v3
	s_waitcnt lgkmcnt(3)
	v_bfe_u32 v4, v16, 16, 1
	v_add3_u32 v4, v16, v4, s41
	s_waitcnt lgkmcnt(2)
	v_bfe_u32 v5, v18, 16, 1
	v_lshrrev_b32_e32 v4, 16, v4
	v_add3_u32 v5, v18, v5, s41
	v_and_or_b32 v4, v5, s42, v4
	s_waitcnt lgkmcnt(1)
	v_bfe_u32 v5, v20, 16, 1
	v_or_b32_e32 v24, s6, v64
	s_ashr_i32 s9, s8, 31
	v_add3_u32 v5, v20, v5, s41
	s_waitcnt lgkmcnt(0)
	v_bfe_u32 v6, v22, 16, 1
	v_ashrrev_i32_e32 v25, 31, v24
	v_lshl_add_u64 v[8:9], s[8:9], 1, v[56:57]
	v_lshrrev_b32_e32 v5, 16, v5
	v_add3_u32 v6, v22, v6, s41
	v_lshlrev_b64 v[24:25], 13, v[24:25]
	v_and_or_b32 v5, v6, s42, v5
	v_lshl_add_u64 v[24:25], v[8:9], 0, v[24:25]
	global_store_dwordx4 v[24:25], v[2:5], off
	v_bfe_u32 v6, v23, 16, 1
	v_add3_u32 v6, v23, v6, s41
	v_bfe_u32 v2, v7, 16, 1
	v_add3_u32 v2, v7, v2, s41
	v_bfe_u32 v3, v11, 16, 1
	v_lshrrev_b32_e32 v2, 16, v2
	v_add3_u32 v3, v11, v3, s41
	v_and_or_b32 v2, v3, s42, v2
	v_bfe_u32 v3, v13, 16, 1
	v_add3_u32 v3, v13, v3, s41
	v_bfe_u32 v4, v15, 16, 1
	v_lshrrev_b32_e32 v3, 16, v3
	v_add3_u32 v4, v15, v4, s41
	v_and_or_b32 v3, v4, s42, v3
	v_bfe_u32 v4, v17, 16, 1
	v_add3_u32 v4, v17, v4, s41
	v_bfe_u32 v5, v19, 16, 1
	v_lshrrev_b32_e32 v4, 16, v4
	v_add3_u32 v5, v19, v5, s41
	v_and_or_b32 v4, v5, s42, v4
	v_bfe_u32 v5, v21, 16, 1
	v_add3_u32 v5, v21, v5, s41
	v_lshrrev_b32_e32 v5, 16, v5
	v_and_or_b32 v5, v6, s42, v5
	v_or_b32_e32 v6, s6, v66
	v_ashrrev_i32_e32 v7, 31, v6
	v_lshlrev_b64 v[6:7], 13, v[6:7]
	ds_read2_b32 v[10:11], v65 offset0:16 offset1:24
	v_lshl_add_u64 v[6:7], v[8:9], 0, v[6:7]
	global_store_dwordx4 v[6:7], v[2:5], off
	ds_read2_b32 v[6:7], v65 offset0:49 offset1:57
	ds_read2_b32 v[12:13], v65 offset0:82 offset1:90
	ds_read2_b32 v[14:15], v65 offset0:115 offset1:123
	s_waitcnt lgkmcnt(3)
	v_bfe_u32 v2, v10, 16, 1
	v_add3_u32 v2, v10, v2, s41
	s_waitcnt lgkmcnt(2)
	v_bfe_u32 v3, v6, 16, 1
	ds_read2_b32 v[16:17], v65 offset0:148 offset1:156
	v_lshrrev_b32_e32 v2, 16, v2
	v_add3_u32 v3, v6, v3, s41
	ds_read2_b32 v[18:19], v65 offset0:181 offset1:189
	v_and_or_b32 v2, v3, s42, v2
	s_waitcnt lgkmcnt(3)
	v_bfe_u32 v3, v12, 16, 1
	v_add3_u32 v3, v12, v3, s41
	s_waitcnt lgkmcnt(2)
	v_bfe_u32 v4, v14, 16, 1
	ds_read2_b32 v[20:21], v65 offset0:214 offset1:222
	v_lshrrev_b32_e32 v3, 16, v3
	v_add3_u32 v4, v14, v4, s41
	ds_read2_b32 v[22:23], v65 offset0:247 offset1:255
	v_and_or_b32 v3, v4, s42, v3
	s_waitcnt lgkmcnt(3)
	v_bfe_u32 v4, v16, 16, 1
	v_add3_u32 v4, v16, v4, s41
	s_waitcnt lgkmcnt(2)
	v_bfe_u32 v5, v18, 16, 1
	v_lshrrev_b32_e32 v4, 16, v4
	v_add3_u32 v5, v18, v5, s41
	v_and_or_b32 v4, v5, s42, v4
	s_waitcnt lgkmcnt(1)
	v_bfe_u32 v5, v20, 16, 1
	v_or_b32_e32 v24, s6, v67
	v_add3_u32 v5, v20, v5, s41
	s_waitcnt lgkmcnt(0)
	v_bfe_u32 v6, v22, 16, 1
	v_ashrrev_i32_e32 v25, 31, v24
	v_lshrrev_b32_e32 v5, 16, v5
	v_add3_u32 v6, v22, v6, s41
	v_lshlrev_b64 v[24:25], 13, v[24:25]
	v_and_or_b32 v5, v6, s42, v5
	v_lshl_add_u64 v[24:25], v[8:9], 0, v[24:25]
	global_store_dwordx4 v[24:25], v[2:5], off
	v_bfe_u32 v6, v23, 16, 1
	v_add3_u32 v6, v23, v6, s41
	v_bfe_u32 v2, v11, 16, 1
	v_add3_u32 v2, v11, v2, s41
	v_bfe_u32 v3, v7, 16, 1
	v_lshrrev_b32_e32 v2, 16, v2
	v_add3_u32 v3, v7, v3, s41
	v_and_or_b32 v2, v3, s42, v2
	v_bfe_u32 v3, v13, 16, 1
	v_add3_u32 v3, v13, v3, s41
	v_bfe_u32 v4, v15, 16, 1
	v_lshrrev_b32_e32 v3, 16, v3
	v_add3_u32 v4, v15, v4, s41
	v_and_or_b32 v3, v4, s42, v3
	v_bfe_u32 v4, v17, 16, 1
	v_add3_u32 v4, v17, v4, s41
	v_bfe_u32 v5, v19, 16, 1
	v_lshrrev_b32_e32 v4, 16, v4
	v_add3_u32 v5, v19, v5, s41
	v_and_or_b32 v4, v5, s42, v4
	v_bfe_u32 v5, v21, 16, 1
	v_add3_u32 v5, v21, v5, s41
	v_lshrrev_b32_e32 v5, 16, v5
	v_and_or_b32 v5, v6, s42, v5
	v_or_b32_e32 v6, s6, v68
	v_ashrrev_i32_e32 v7, 31, v6
	v_lshlrev_b64 v[6:7], 13, v[6:7]
	v_lshl_add_u64 v[6:7], v[8:9], 0, v[6:7]
	global_store_dwordx4 v[6:7], v[2:5], off
	s_waitcnt lgkmcnt(0)
	s_branch .LBB0_11
